# ssd_s3 tile epilogue: the eight gate fragments and eight RMSNorm gain vectors are requested together (were sixteen load-wait-use steps)
# speedup vs baseline: 1.0059x; 1.0059x over previous
.LBB0_2294:
	s_or_b64 exec, exec, s[30:31]
	v_add_u32_e32 v6, 0x22000, v77
	ds_read2st64_b32 v[6:7], v6 offset1:4
	v_lshl_add_u64 v[44:45], v[118:119], 0, v[10:11]
	global_load_dwordx2 v[28:29], v11, s[62:63]
	v_mad_u64_u32 v[46:47], s[4:5], v120, s81, v[70:71]
	s_waitcnt lgkmcnt(0)
	v_div_scale_f32 v8, s[4:5], v6, v6, 1.0
	v_rcp_f32_e32 v9, v8
	ds_read2_b64 v[52:55], v46 offset1:4
	v_mov_b32_e32 v103, v11
	v_mov_b32_e32 v105, v11
	v_fma_f32 v24, -v8, v9, 1.0
	v_fmac_f32_e32 v9, v24, v9
	v_div_scale_f32 v24, vcc, 1.0, v6, 1.0
	v_mul_f32_e32 v25, v24, v9
	v_fma_f32 v26, -v8, v25, v24
	v_fmac_f32_e32 v25, v26, v9
	v_fma_f32 v8, -v8, v25, v24
	v_div_fmas_f32 v8, v8, v9, v25
	v_div_fixup_f32 v6, v8, v6, 1.0
	global_load_dwordx2 v[150:151], v[44:45], off offset:3584
	global_load_dwordx2 v[152:153], v[44:45], off offset:3616
	global_load_dwordx2 v[154:155], v[44:45], off offset:3648
	global_load_dwordx2 v[156:157], v[44:45], off offset:3680
	global_load_dwordx2 v[158:159], v[44:45], off offset:3712
	global_load_dwordx2 v[160:161], v[44:45], off offset:3744
	global_load_dwordx2 v[162:163], v[44:45], off offset:3776
	global_load_dwordx2 v[164:165], v[44:45], off offset:3808
	global_load_dwordx4 v[166:169], v[84:85], off
	global_load_dwordx4 v[170:173], v[84:85], off offset:64
	global_load_dwordx4 v[182:185], v[84:85], off offset:128
	global_load_dwordx4 v[186:189], v[84:85], off offset:192
	global_load_dwordx4 v[190:193], v[84:85], off offset:256
	global_load_dwordx4 v[194:197], v[84:85], off offset:320
	global_load_dwordx4 v[198:201], v[84:85], off offset:384
	global_load_dwordx4 v[214:217], v[84:85], off offset:448
	s_waitcnt lgkmcnt(0)
	v_and_b32_e32 v27, 0xffff0000, v52
	v_lshlrev_b32_e32 v26, 16, v52
	v_mov_b32_e32 v107, v11
	v_mov_b32_e32 v109, v11
	v_mov_b32_e32 v111, v11
	v_mov_b32_e32 v113, v11
	v_mov_b32_e32 v115, v11
	s_waitcnt vmcnt(16)
	v_pk_mul_f32 v[26:27], v[28:29], v[26:27] op_sel_hi:[0,1]
	v_pk_fma_f32 v[26:27], v[6:7], v[26:27], v[48:49] op_sel_hi:[0,1,1]
	s_waitcnt vmcnt(15)
	v_lshlrev_b32_e32 v24, 16, v150
	v_and_b32_e32 v25, 0xffff0000, v150
	v_mul_f32_e32 v8, 0xbfb8aa3b, v24
	v_exp_f32_e32 v8, v8
	s_nop 0
	v_add_f32_e32 v8, 1.0, v8
	v_rcp_f32_e32 v30, v8
	v_mul_f32_e32 v8, 0xbfb8aa3b, v25
	v_exp_f32_e32 v8, v8
	s_nop 0
	v_add_f32_e32 v8, 1.0, v8
	v_rcp_f32_e32 v31, v8
	s_nop 0
	v_pk_mul_f32 v[24:25], v[30:31], v[24:25]
	s_nop 0
	v_pk_mul_f32 v[24:25], v[26:27], v[24:25]
	v_lshlrev_b32_e32 v26, 16, v151
	v_mul_f32_e32 v47, 0xbfb8aa3b, v26
	v_exp_f32_e32 v47, v47
	v_and_b32_e32 v27, 0xffff0000, v151
	v_mul_f32_e32 v8, v25, v25
	v_mov_b32_e32 v9, v151
	v_pk_fma_f32 v[30:31], v[24:25], v[24:25], v[8:9] op_sel_hi:[1, 1, 0]
	v_add_f32_e32 v47, 1.0, v47
	v_rcp_f32_e32 v48, v47
	v_mul_f32_e32 v47, 0xbfb8aa3b, v27
	v_exp_f32_e32 v47, v47
	v_and_b32_e32 v9, 0xffff0000, v53
	v_lshlrev_b32_e32 v8, 16, v53
	v_pk_mul_f32 v[8:9], v[28:29], v[8:9] op_sel_hi:[0,1]
	v_add_f32_e32 v47, 1.0, v47
	v_rcp_f32_e32 v49, v47
	v_pk_fma_f32 v[8:9], v[6:7], v[8:9], v[50:51] op_sel_hi:[0,1,1]
	v_and_b32_e32 v51, 0xffff0000, v54
	v_lshlrev_b32_e32 v50, 16, v54
	v_pk_mul_f32 v[26:27], v[48:49], v[26:27]
	s_nop 0
	v_pk_mul_f32 v[26:27], v[8:9], v[26:27]
	v_pk_mul_f32 v[50:51], v[28:29], v[50:51] op_sel_hi:[0,1]
	v_pk_fma_f32 v[8:9], v[26:27], v[26:27], v[30:31]
	v_mul_f32_e32 v30, v27, v27
	v_pk_add_f32 v[8:9], v[30:31], v[8:9] op_sel_hi:[0,1]
	v_pk_fma_f32 v[40:41], v[6:7], v[50:51], v[40:41] op_sel_hi:[0,1,1]
	s_waitcnt vmcnt(14)
	v_lshlrev_b32_e32 v30, 16, v152
	v_mul_f32_e32 v47, 0xbfb8aa3b, v30
	v_exp_f32_e32 v47, v47
	v_and_b32_e32 v31, 0xffff0000, v152
	v_lshlrev_b32_e32 v48, 16, v55
	v_add_f32_e32 v47, 1.0, v47
	v_rcp_f32_e32 v52, v47
	v_mul_f32_e32 v47, 0xbfb8aa3b, v31
	v_exp_f32_e32 v47, v47
	s_nop 0
	v_add_f32_e32 v47, 1.0, v47
	v_rcp_f32_e32 v53, v47
	s_nop 0
	v_pk_mul_f32 v[30:31], v[52:53], v[30:31]
	s_nop 0
	v_pk_mul_f32 v[30:31], v[40:41], v[30:31]
	s_nop 0
	v_pk_fma_f32 v[8:9], v[30:31], v[30:31], v[8:9]
	v_mul_f32_e32 v40, v31, v31
	v_pk_add_f32 v[8:9], v[40:41], v[8:9] op_sel_hi:[0,1]
	v_lshlrev_b32_e32 v40, 16, v153
	v_mul_f32_e32 v47, 0xbfb8aa3b, v40
	v_exp_f32_e32 v47, v47
	v_and_b32_e32 v41, 0xffff0000, v153
	v_and_b32_e32 v49, 0xffff0000, v55
	v_pk_mul_f32 v[48:49], v[28:29], v[48:49] op_sel_hi:[0,1]
	v_add_f32_e32 v47, 1.0, v47
	v_rcp_f32_e32 v50, v47
	v_mul_f32_e32 v47, 0xbfb8aa3b, v41
	v_exp_f32_e32 v47, v47
	v_pk_fma_f32 v[42:43], v[6:7], v[48:49], v[42:43] op_sel_hi:[0,1,1]
	v_add_f32_e32 v47, 1.0, v47
	v_rcp_f32_e32 v51, v47
	s_nop 0
	v_pk_mul_f32 v[40:41], v[50:51], v[40:41]
	s_nop 0
	v_pk_mul_f32 v[40:41], v[42:43], v[40:41]
	ds_read2_b64 v[48:51], v46 offset0:8 offset1:12
	v_pk_fma_f32 v[8:9], v[40:41], v[40:41], v[8:9]
	v_mul_f32_e32 v42, v41, v41
	v_pk_add_f32 v[8:9], v[42:43], v[8:9] op_sel_hi:[0,1]
	s_nop 0
	s_waitcnt lgkmcnt(0)
	v_and_b32_e32 v55, 0xffff0000, v48
	v_lshlrev_b32_e32 v54, 16, v48
	v_pk_mul_f32 v[54:55], v[28:29], v[54:55] op_sel_hi:[0,1]
	v_pk_fma_f32 v[36:37], v[6:7], v[54:55], v[36:37] op_sel_hi:[0,1,1]
	s_waitcnt vmcnt(13)
	v_lshlrev_b32_e32 v52, 16, v154
	v_and_b32_e32 v53, 0xffff0000, v154
	v_mul_f32_e32 v42, 0xbfb8aa3b, v52
	v_exp_f32_e32 v42, v42
	s_nop 0
	v_add_f32_e32 v42, 1.0, v42
	v_rcp_f32_e32 v56, v42
	v_mul_f32_e32 v42, 0xbfb8aa3b, v53
	v_exp_f32_e32 v42, v42
	s_nop 0
	v_add_f32_e32 v42, 1.0, v42
	v_rcp_f32_e32 v57, v42
	s_nop 0
	v_pk_mul_f32 v[52:53], v[56:57], v[52:53]
	s_nop 0
	v_pk_mul_f32 v[36:37], v[36:37], v[52:53]
	v_and_b32_e32 v53, 0xffff0000, v155
	v_pk_fma_f32 v[8:9], v[36:37], v[36:37], v[8:9]
	v_mul_f32_e32 v42, v37, v37
	v_mov_b32_e32 v43, v155
	v_pk_add_f32 v[8:9], v[42:43], v[8:9] op_sel_hi:[0, 1]
	v_lshlrev_b32_e32 v52, 16, v43
	v_and_b32_e32 v43, 0xffff0000, v49
	v_lshlrev_b32_e32 v42, 16, v49
	v_pk_mul_f32 v[42:43], v[28:29], v[42:43] op_sel_hi:[0,1]
	v_mul_f32_e32 v47, 0xbfb8aa3b, v52
	v_pk_fma_f32 v[38:39], v[6:7], v[42:43], v[38:39] op_sel_hi:[0,1,1]
	v_mul_f32_e32 v42, 0xbfb8aa3b, v53
	v_exp_f32_e32 v47, v47
	v_exp_f32_e32 v42, v42
	v_add_f32_e32 v47, 1.0, v47
	v_add_f32_e32 v42, 1.0, v42
	v_rcp_f32_e32 v48, v47
	v_rcp_f32_e32 v49, v42
	s_nop 0
	v_pk_mul_f32 v[42:43], v[48:49], v[52:53]
	s_nop 0
	v_pk_mul_f32 v[38:39], v[38:39], v[42:43]
	v_and_b32_e32 v53, 0xffff0000, v50
	v_pk_fma_f32 v[8:9], v[38:39], v[38:39], v[8:9]
	v_mul_f32_e32 v42, v39, v39
	v_pk_add_f32 v[8:9], v[42:43], v[8:9] op_sel_hi:[0,1]
	s_nop 0
	v_lshlrev_b32_e32 v52, 16, v50
	v_pk_mul_f32 v[52:53], v[28:29], v[52:53] op_sel_hi:[0,1]
	v_pk_fma_f32 v[32:33], v[6:7], v[52:53], v[32:33] op_sel_hi:[0,1,1]
	s_waitcnt vmcnt(12)
	v_lshlrev_b32_e32 v48, 16, v156
	v_and_b32_e32 v49, 0xffff0000, v156
	v_mul_f32_e32 v42, 0xbfb8aa3b, v48
	v_exp_f32_e32 v42, v42
	s_nop 0
	v_add_f32_e32 v42, 1.0, v42
	v_rcp_f32_e32 v54, v42
	v_mul_f32_e32 v42, 0xbfb8aa3b, v49
	v_exp_f32_e32 v42, v42
	s_nop 0
	v_add_f32_e32 v42, 1.0, v42
	v_rcp_f32_e32 v55, v42
	s_nop 0
	v_pk_mul_f32 v[48:49], v[54:55], v[48:49]
	s_nop 0
	v_pk_mul_f32 v[32:33], v[32:33], v[48:49]
	v_and_b32_e32 v49, 0xffff0000, v157
	v_pk_fma_f32 v[8:9], v[32:33], v[32:33], v[8:9]
	v_mul_f32_e32 v42, v33, v33
	v_mov_b32_e32 v43, v157
	v_pk_add_f32 v[8:9], v[42:43], v[8:9] op_sel_hi:[0, 1]
	v_lshlrev_b32_e32 v48, 16, v43
	v_and_b32_e32 v43, 0xffff0000, v51
	v_lshlrev_b32_e32 v42, 16, v51
	v_pk_mul_f32 v[42:43], v[28:29], v[42:43] op_sel_hi:[0,1]
	v_mul_f32_e32 v47, 0xbfb8aa3b, v48
	v_pk_fma_f32 v[34:35], v[6:7], v[42:43], v[34:35] op_sel_hi:[0,1,1]
	v_mul_f32_e32 v6, 0xbfb8aa3b, v49
	v_exp_f32_e32 v47, v47
	v_exp_f32_e32 v6, v6
	v_add_f32_e32 v47, 1.0, v47
	v_add_f32_e32 v6, 1.0, v6
	v_rcp_f32_e32 v50, v47
	v_rcp_f32_e32 v51, v6
	s_nop 0
	v_pk_mul_f32 v[42:43], v[50:51], v[48:49]
	s_nop 0
	v_pk_mul_f32 v[34:35], v[34:35], v[42:43]
	s_waitcnt vmcnt(11)
	v_lshlrev_b32_e32 v52, 16, v158
	v_pk_fma_f32 v[8:9], v[34:35], v[34:35], v[8:9]
	v_mul_f32_e32 v6, v35, v35
	v_pk_add_f32 v[48:49], v[6:7], v[8:9] op_sel_hi:[0,1]
	v_div_scale_f32 v6, s[4:5], v7, v7, 1.0
	v_rcp_f32_e32 v8, v6
	v_and_b32_e32 v53, 0xffff0000, v158
	s_mov_b64 s[4:5], 0x5800600
	v_fma_f32 v9, -v6, v8, 1.0
	v_fmac_f32_e32 v8, v9, v8
	v_div_scale_f32 v9, vcc, 1.0, v7, 1.0
	v_mul_f32_e32 v42, v9, v8
	v_fma_f32 v43, -v6, v42, v9
	v_fmac_f32_e32 v42, v43, v8
	v_fma_f32 v6, -v6, v42, v9
	v_div_fmas_f32 v6, v6, v8, v42
	v_div_fixup_f32 v42, v6, v7, 1.0
	ds_read2_b64 v[6:9], v46 offset0:16 offset1:20
	s_waitcnt lgkmcnt(0)
	v_and_b32_e32 v55, 0xffff0000, v6
	v_lshlrev_b32_e32 v54, 16, v6
	v_mul_f32_e32 v6, 0xbfb8aa3b, v52
	v_exp_f32_e32 v6, v6
	v_pk_mul_f32 v[54:55], v[28:29], v[54:55] op_sel:[1,0]
	v_lshlrev_b32_e32 v50, 16, v7
	v_pk_fma_f32 v[20:21], v[42:43], v[54:55], v[20:21] op_sel_hi:[0,1,1]
	v_add_f32_e32 v6, 1.0, v6
	v_rcp_f32_e32 v56, v6
	v_mul_f32_e32 v6, 0xbfb8aa3b, v53
	v_exp_f32_e32 v6, v6
	s_nop 0
	v_add_f32_e32 v6, 1.0, v6
	v_rcp_f32_e32 v57, v6
	s_nop 0
	v_pk_mul_f32 v[52:53], v[56:57], v[52:53]
	s_nop 0
	v_pk_mul_f32 v[20:21], v[20:21], v[52:53]
	v_and_b32_e32 v53, 0xffff0000, v159
	v_pk_fma_f32 v[48:49], v[20:21], v[20:21], v[48:49]
	v_mul_f32_e32 v6, v21, v21
	v_lshlrev_b32_e32 v52, 16, v159
	v_pk_add_f32 v[48:49], v[6:7], v[48:49] op_sel_hi:[0,1]
	v_and_b32_e32 v51, 0xffff0000, v7
	v_mul_f32_e32 v6, 0xbfb8aa3b, v52
	v_mul_f32_e32 v7, 0xbfb8aa3b, v53
	v_exp_f32_e32 v6, v6
	v_exp_f32_e32 v7, v7
	v_pk_mul_f32 v[50:51], v[28:29], v[50:51] op_sel:[1,0]
	v_add_f32_e32 v6, 1.0, v6
	v_add_f32_e32 v7, 1.0, v7
	v_rcp_f32_e32 v6, v6
	v_rcp_f32_e32 v7, v7
	v_pk_fma_f32 v[22:23], v[42:43], v[50:51], v[22:23] op_sel_hi:[0,1,1]
	v_pk_mul_f32 v[6:7], v[6:7], v[52:53]
	s_nop 0
	v_pk_mul_f32 v[22:23], v[22:23], v[6:7]
	v_and_b32_e32 v53, 0xffff0000, v8
	v_pk_fma_f32 v[6:7], v[22:23], v[22:23], v[48:49]
	v_mul_f32_e32 v48, v23, v23
	v_pk_add_f32 v[6:7], v[48:49], v[6:7] op_sel_hi:[0,1]
	s_nop 0
	v_lshlrev_b32_e32 v52, 16, v8
	v_pk_mul_f32 v[52:53], v[28:29], v[52:53] op_sel:[1,0]
	s_waitcnt vmcnt(10)
	v_lshlrev_b32_e32 v50, 16, v160
	v_mul_f32_e32 v8, 0xbfb8aa3b, v50
	v_exp_f32_e32 v8, v8
	v_and_b32_e32 v51, 0xffff0000, v160
	v_pk_fma_f32 v[16:17], v[42:43], v[52:53], v[16:17] op_sel_hi:[0,1,1]
	v_lshlrev_b32_e32 v48, 16, v9
	v_add_f32_e32 v8, 1.0, v8
	v_rcp_f32_e32 v54, v8
	v_mul_f32_e32 v8, 0xbfb8aa3b, v51
	v_exp_f32_e32 v8, v8
	s_nop 0
	v_add_f32_e32 v8, 1.0, v8
	v_rcp_f32_e32 v55, v8
	s_nop 0
	v_pk_mul_f32 v[50:51], v[54:55], v[50:51]
	s_nop 0
	v_pk_mul_f32 v[16:17], v[16:17], v[50:51]
	v_and_b32_e32 v51, 0xffff0000, v161
	v_pk_fma_f32 v[6:7], v[16:17], v[16:17], v[6:7]
	v_mul_f32_e32 v8, v17, v17
	v_lshlrev_b32_e32 v50, 16, v161
	v_pk_add_f32 v[6:7], v[8:9], v[6:7] op_sel_hi:[0,1]
	v_and_b32_e32 v49, 0xffff0000, v9
	v_mul_f32_e32 v8, 0xbfb8aa3b, v50
	v_mul_f32_e32 v9, 0xbfb8aa3b, v51
	v_exp_f32_e32 v8, v8
	v_exp_f32_e32 v9, v9
	v_pk_mul_f32 v[48:49], v[28:29], v[48:49] op_sel:[1,0]
	v_add_f32_e32 v8, 1.0, v8
	v_add_f32_e32 v9, 1.0, v9
	v_rcp_f32_e32 v8, v8
	v_rcp_f32_e32 v9, v9
	v_pk_fma_f32 v[18:19], v[42:43], v[48:49], v[18:19] op_sel_hi:[0,1,1]
	v_pk_mul_f32 v[8:9], v[8:9], v[50:51]
	s_nop 0
	v_pk_mul_f32 v[18:19], v[18:19], v[8:9]
	s_nop 0
	v_pk_fma_f32 v[6:7], v[18:19], v[18:19], v[6:7]
	v_mul_f32_e32 v8, v19, v19
	v_pk_add_f32 v[48:49], v[8:9], v[6:7] op_sel_hi:[0,1]
	ds_read2_b64 v[6:9], v46 offset0:24 offset1:28
	s_waitcnt lgkmcnt(0)
	v_and_b32_e32 v53, 0xffff0000, v6
	v_lshlrev_b32_e32 v52, 16, v6
	v_pk_mul_f32 v[52:53], v[28:29], v[52:53] op_sel:[1,0]
	s_waitcnt vmcnt(9)
	v_lshlrev_b32_e32 v46, 16, v162
	v_mul_f32_e32 v6, 0xbfb8aa3b, v46
	v_exp_f32_e32 v6, v6
	v_and_b32_e32 v47, 0xffff0000, v162
	v_pk_fma_f32 v[12:13], v[42:43], v[52:53], v[12:13] op_sel_hi:[0,1,1]
	v_lshlrev_b32_e32 v50, 16, v7
	v_add_f32_e32 v6, 1.0, v6
	v_rcp_f32_e32 v54, v6
	v_mul_f32_e32 v6, 0xbfb8aa3b, v47
	v_exp_f32_e32 v6, v6
	s_nop 0
	v_add_f32_e32 v6, 1.0, v6
	v_rcp_f32_e32 v55, v6
	s_nop 0
	v_pk_mul_f32 v[46:47], v[54:55], v[46:47]
	s_nop 0
	v_pk_mul_f32 v[12:13], v[12:13], v[46:47]
	s_nop 0
	v_pk_fma_f32 v[46:47], v[12:13], v[12:13], v[48:49]
	v_mul_f32_e32 v6, v13, v13
	v_and_b32_e32 v49, 0xffff0000, v163
	v_lshlrev_b32_e32 v48, 16, v163
	v_pk_add_f32 v[46:47], v[6:7], v[46:47] op_sel_hi:[0,1]
	v_and_b32_e32 v51, 0xffff0000, v7
	v_mul_f32_e32 v6, 0xbfb8aa3b, v48
	v_mul_f32_e32 v7, 0xbfb8aa3b, v49
	v_exp_f32_e32 v6, v6
	v_exp_f32_e32 v7, v7
	v_pk_mul_f32 v[50:51], v[28:29], v[50:51] op_sel:[1,0]
	v_add_f32_e32 v6, 1.0, v6
	v_add_f32_e32 v7, 1.0, v7
	v_rcp_f32_e32 v6, v6
	v_rcp_f32_e32 v7, v7
	v_pk_fma_f32 v[14:15], v[42:43], v[50:51], v[14:15] op_sel_hi:[0,1,1]
	v_pk_mul_f32 v[6:7], v[6:7], v[48:49]
	s_nop 0
	v_pk_mul_f32 v[6:7], v[14:15], v[6:7]
	v_and_b32_e32 v49, 0xffff0000, v8
	v_pk_fma_f32 v[14:15], v[6:7], v[6:7], v[46:47]
	v_mul_f32_e32 v46, v7, v7
	v_pk_add_f32 v[14:15], v[46:47], v[14:15] op_sel_hi:[0,1]
	s_waitcnt vmcnt(8)
	v_lshlrev_b32_e32 v46, 16, v164
	v_lshlrev_b32_e32 v48, 16, v8
	v_mul_f32_e32 v8, 0xbfb8aa3b, v46
	v_exp_f32_e32 v8, v8
	v_and_b32_e32 v47, 0xffff0000, v164
	v_pk_mul_f32 v[48:49], v[28:29], v[48:49] op_sel:[1,0]
	v_lshlrev_b32_e32 v44, 16, v9
	v_add_f32_e32 v8, 1.0, v8
	v_rcp_f32_e32 v50, v8
	v_mul_f32_e32 v8, 0xbfb8aa3b, v47
	v_exp_f32_e32 v8, v8
	v_pk_fma_f32 v[2:3], v[42:43], v[48:49], v[2:3] op_sel_hi:[0,1,1]
	v_add_f32_e32 v8, 1.0, v8
	v_rcp_f32_e32 v51, v8
	s_nop 0
	v_pk_mul_f32 v[46:47], v[50:51], v[46:47]
	s_nop 0
	v_pk_mul_f32 v[2:3], v[2:3], v[46:47]
	v_and_b32_e32 v47, 0xffff0000, v165
	v_pk_fma_f32 v[14:15], v[2:3], v[2:3], v[14:15]
	v_mul_f32_e32 v8, v3, v3
	v_lshlrev_b32_e32 v46, 16, v165
	v_pk_add_f32 v[14:15], v[8:9], v[14:15] op_sel_hi:[0,1]
	v_and_b32_e32 v45, 0xffff0000, v9
	v_mul_f32_e32 v8, 0xbfb8aa3b, v46
	v_mul_f32_e32 v9, 0xbfb8aa3b, v47
	v_exp_f32_e32 v8, v8
	v_exp_f32_e32 v9, v9
	v_pk_mul_f32 v[28:29], v[28:29], v[44:45] op_sel:[1,0]
	v_add_f32_e32 v8, 1.0, v8
	v_add_f32_e32 v9, 1.0, v9
	v_rcp_f32_e32 v8, v8
	v_rcp_f32_e32 v9, v9
	v_pk_fma_f32 v[4:5], v[42:43], v[28:29], v[4:5] op_sel_hi:[0,1,1]
	v_pk_mul_f32 v[8:9], v[8:9], v[46:47]
	s_nop 0
	v_pk_mul_f32 v[8:9], v[4:5], v[8:9]
	s_nop 0
	v_pk_fma_f32 v[4:5], v[8:9], v[8:9], v[14:15]
	v_mul_f32_e32 v14, v9, v9
	v_pk_add_f32 v[4:5], v[14:15], v[4:5] op_sel_hi:[0,1]
	v_mov_b32_e32 v5, v4
	s_nop 1
	v_permlane16_swap_b32 v4, v5
	s_nop 1
	s_nop 0
	v_add_f32_e32 v4, v4, v5
	v_mov_b32_e32 v5, v4
	s_nop 1
	v_permlane32_swap_b32 v4, v5
	s_nop 1
	s_nop 0
	v_add_f32_e32 v4, v4, v5
	v_fmamk_f32 v4, v4, 0x3c000000, v174
	v_cmp_gt_f32_e32 vcc, s52, v4
	v_mul_f32_e32 v5, 0x4b800000, v4
	s_nop 0
	v_cndmask_b32_e32 v4, v4, v5, vcc
	v_rsq_f32_e32 v4, v4
	s_nop 0
	v_mul_f32_e32 v5, 0x45800000, v4
	v_cndmask_b32_e32 v14, v4, v5, vcc
	v_lshlrev_b64 v[4:5], 11, v[116:117]
	v_lshl_add_u64 v[4:5], s[90:91], 0, v[4:5]
	v_pk_mul_f32 v[24:25], v[24:25], v[14:15] op_sel_hi:[1,0]
	v_pk_mul_f32 v[26:27], v[26:27], v[14:15] op_sel_hi:[1,0]
	v_lshl_add_u64 v[4:5], v[4:5], 0, s[4:5]
	v_pk_mul_f32 v[28:29], v[30:31], v[14:15] op_sel_hi:[1,0]
	v_pk_mul_f32 v[30:31], v[40:41], v[14:15] op_sel_hi:[1,0]
	v_pk_mul_f32 v[20:21], v[20:21], v[14:15] op_sel_hi:[1,0]
	v_pk_mul_f32 v[22:23], v[22:23], v[14:15] op_sel_hi:[1,0]
	v_pk_mul_f32 v[16:17], v[16:17], v[14:15] op_sel_hi:[1,0]
	v_pk_mul_f32 v[18:19], v[18:19], v[14:15] op_sel_hi:[1,0]
	v_pk_mul_f32 v[12:13], v[12:13], v[14:15] op_sel_hi:[1,0]
	v_pk_mul_f32 v[6:7], v[6:7], v[14:15] op_sel_hi:[1,0]
	v_pk_mul_f32 v[2:3], v[2:3], v[14:15] op_sel_hi:[1,0]
	v_cmp_lt_i32_e32 vcc, 7, v75
	s_or_b64 s[40:41], vcc, s[40:41]
	s_waitcnt vmcnt(7)
	v_pk_mul_f32 v[26:27], v[168:169], v[26:27]
	v_pk_mul_f32 v[24:25], v[166:167], v[24:25]
	s_nop 0
	v_cvt_pk_bf16_f32 v24, v24, v25
	v_cvt_pk_bf16_f32 v25, v26, v27
	v_lshl_add_u64 v[26:27], v[4:5], 0, v[10:11]
	global_store_dwordx2 v[26:27], v[24:25], off
	s_nop 0
	s_waitcnt vmcnt(6)
	v_pk_mul_f32 v[26:27], v[172:173], v[30:31]
	v_pk_mul_f32 v[24:25], v[170:171], v[28:29]
	v_pk_mul_f32 v[28:29], v[36:37], v[14:15] op_sel_hi:[1,0]
	v_cvt_pk_bf16_f32 v24, v24, v25
	v_cvt_pk_bf16_f32 v25, v26, v27
	v_lshl_add_u64 v[26:27], v[4:5], 0, v[102:103]
	global_store_dwordx2 v[26:27], v[24:25], off
	s_nop 0
	v_pk_mul_f32 v[30:31], v[38:39], v[14:15] op_sel_hi:[1,0]
	s_waitcnt vmcnt(5)
	v_pk_mul_f32 v[24:25], v[182:183], v[28:29]
	v_pk_mul_f32 v[26:27], v[184:185], v[30:31]
	v_cvt_pk_bf16_f32 v24, v24, v25
	v_pk_mul_f32 v[28:29], v[32:33], v[14:15] op_sel_hi:[1,0]
	v_cvt_pk_bf16_f32 v25, v26, v27
	v_lshl_add_u64 v[26:27], v[4:5], 0, v[104:105]
	global_store_dwordx2 v[26:27], v[24:25], off
	s_nop 0
	v_pk_mul_f32 v[30:31], v[34:35], v[14:15] op_sel_hi:[1,0]
	s_waitcnt vmcnt(4)
	v_pk_mul_f32 v[24:25], v[186:187], v[28:29]
	v_pk_mul_f32 v[26:27], v[188:189], v[30:31]
	v_cvt_pk_bf16_f32 v24, v24, v25
	s_nop 0
	v_cvt_pk_bf16_f32 v25, v26, v27
	v_lshl_add_u64 v[26:27], v[4:5], 0, v[106:107]
	global_store_dwordx2 v[26:27], v[24:25], off
	s_nop 0
	s_waitcnt vmcnt(3)
	v_pk_mul_f32 v[22:23], v[22:23], v[192:193]
	v_pk_mul_f32 v[20:21], v[20:21], v[190:191]
	s_nop 0
	v_cvt_pk_bf16_f32 v20, v20, v21
	v_cvt_pk_bf16_f32 v21, v22, v23
	v_lshl_add_u64 v[22:23], v[4:5], 0, v[108:109]
	global_store_dwordx2 v[22:23], v[20:21], off
	s_nop 0
	s_waitcnt vmcnt(2)
	v_pk_mul_f32 v[18:19], v[18:19], v[196:197]
	v_pk_mul_f32 v[16:17], v[16:17], v[194:195]
	s_nop 0
	v_cvt_pk_bf16_f32 v16, v16, v17
	v_cvt_pk_bf16_f32 v17, v18, v19
	v_lshl_add_u64 v[18:19], v[4:5], 0, v[110:111]
	global_store_dwordx2 v[18:19], v[16:17], off
	s_nop 0
	s_waitcnt vmcnt(1)
	v_pk_mul_f32 v[6:7], v[6:7], v[200:201]
	v_pk_mul_f32 v[12:13], v[12:13], v[198:199]
	s_nop 0
	v_cvt_pk_bf16_f32 v12, v12, v13
	v_cvt_pk_bf16_f32 v13, v6, v7
	v_lshl_add_u64 v[6:7], v[4:5], 0, v[112:113]
	global_store_dwordx2 v[6:7], v[12:13], off
	s_nop 0
	v_pk_mul_f32 v[6:7], v[8:9], v[14:15] op_sel_hi:[1,0]
	v_lshl_add_u64 v[4:5], v[4:5], 0, v[114:115]
	s_waitcnt vmcnt(0)
	v_pk_mul_f32 v[2:3], v[2:3], v[214:215]
	s_nop 0
	v_cvt_pk_bf16_f32 v2, v2, v3
	v_pk_mul_f32 v[6:7], v[6:7], v[216:217]
	s_nop 0
	v_cvt_pk_bf16_f32 v3, v6, v7
	global_store_dwordx2 v[4:5], v[2:3], off
	v_add_u32_e32 v2, 8, v75
	v_mov_b32_e32 v75, v2
	s_andn2_b64 exec, exec, s[40:41]
	s_cbranch_execz .LBB0_2258
